# grid barrier: workgroups that are not their XCC's last arriver issue the agent acquire (buffer_inv sc1) on arrival, ahead of the wait for the release word (no L1-allocating load in between), so its la
# speedup vs baseline: 1.0072x; 1.0072x over previous
.LBB0_113:
	s_or_b64 exec, exec, s[4:5]
	v_cvt_f32_u32_e32 v4, v2
	s_waitcnt vmcnt(0)
	v_readfirstlane_b32 s3, v3
	v_sub_u32_e32 v3, 0, v2
	v_rcp_iflag_f32_e32 v4, v4
	v_add_u32_e32 v5, s3, v1
	v_mul_f32_e32 v4, 0x4f7ffffe, v4
	v_cvt_u32_f32_e32 v4, v4
	v_mul_lo_u32 v1, v3, v4
	v_mul_hi_u32 v1, v4, v1
	v_add_u32_e32 v1, v4, v1
	v_mul_hi_u32 v1, v5, v1
	v_mul_lo_u32 v3, v1, v2
	v_sub_u32_e32 v3, v5, v3
	v_add_u32_e32 v4, 1, v1
	v_cmp_ge_u32_e32 vcc, v3, v2
	s_nop 1
	v_cndmask_b32_e32 v1, v1, v4, vcc
	v_sub_u32_e32 v4, v3, v2
	v_cndmask_b32_e32 v3, v3, v4, vcc
	v_add_u32_e32 v4, 1, v1
	v_cmp_ge_u32_e32 vcc, v3, v2
	v_add_u32_e32 v3, 1, v5
	s_nop 0
	v_cndmask_b32_e32 v1, v1, v4, vcc
	v_mul_lo_u32 v4, v2, v1
	v_add_u32_e32 v2, v4, v2
	v_cmp_ne_u32_e32 vcc, v3, v2
	s_and_saveexec_b64 s[4:5], vcc
	s_xor_b64 s[4:5], exec, s[4:5]
	s_cbranch_execz .LBB0_127
	s_waitcnt lgkmcnt(0)
	v_mov_b32_e32 v0, 0
	buffer_inv sc1
	global_load_dword v2, v0, s[20:21] sc1
	s_waitcnt vmcnt(0)
	v_cmp_eq_u32_e32 vcc, v2, v1
	s_and_saveexec_b64 s[6:7], vcc
	s_cbranch_execz .LBB0_126
	s_mov_b32 s3, 1
	s_mov_b64 s[8:9], 0
	s_branch .LBB0_117

.LBB0_126:
	s_or_b64 exec, exec, s[6:7]
	s_waitcnt vmcnt(0)
	s_nop 0
	s_waitcnt vmcnt(0)

.LBB0_398:
	s_or_b64 exec, exec, s[4:5]
	v_cvt_f32_u32_e32 v4, v2
	s_waitcnt vmcnt(0)
	v_readfirstlane_b32 s4, v3
	v_sub_u32_e32 v3, 0, v2
	v_rcp_iflag_f32_e32 v4, v4
	v_add_u32_e32 v5, s4, v1
	v_mul_f32_e32 v4, 0x4f7ffffe, v4
	v_cvt_u32_f32_e32 v4, v4
	v_mul_lo_u32 v1, v3, v4
	v_mul_hi_u32 v1, v4, v1
	v_add_u32_e32 v1, v4, v1
	v_mul_hi_u32 v1, v5, v1
	v_mul_lo_u32 v3, v1, v2
	v_sub_u32_e32 v3, v5, v3
	v_add_u32_e32 v4, 1, v1
	v_cmp_ge_u32_e32 vcc, v3, v2
	s_nop 1
	v_cndmask_b32_e32 v1, v1, v4, vcc
	v_sub_u32_e32 v4, v3, v2
	v_cndmask_b32_e32 v3, v3, v4, vcc
	v_add_u32_e32 v4, 1, v1
	v_cmp_ge_u32_e32 vcc, v3, v2
	v_add_u32_e32 v3, 1, v5
	s_nop 0
	v_cndmask_b32_e32 v1, v1, v4, vcc
	v_mul_lo_u32 v4, v2, v1
	v_add_u32_e32 v2, v4, v2
	v_cmp_ne_u32_e32 vcc, v3, v2
	s_and_saveexec_b64 s[4:5], vcc
	s_xor_b64 s[4:5], exec, s[4:5]
	s_cbranch_execz .LBB0_412
	v_readlane_b32 s6, v255, 0
	s_waitcnt lgkmcnt(0)
	v_mov_b32_e32 v0, 0
	v_readlane_b32 s7, v255, 1
	s_nop 4
	buffer_inv sc1
	global_load_dword v2, v0, s[6:7] sc1
	s_waitcnt vmcnt(0)
	v_cmp_eq_u32_e32 vcc, v2, v1
	s_and_saveexec_b64 s[6:7], vcc
	s_cbranch_execz .LBB0_411
	s_mov_b32 s22, 1
	s_mov_b64 s[12:13], 0
	s_branch .LBB0_402

.LBB0_545:
	s_or_b64 exec, exec, s[4:5]
	v_cvt_f32_u32_e32 v4, v2
	s_waitcnt vmcnt(0)
	v_readfirstlane_b32 s4, v3
	v_sub_u32_e32 v3, 0, v2
	v_rcp_iflag_f32_e32 v4, v4
	v_add_u32_e32 v5, s4, v1
	v_mul_f32_e32 v4, 0x4f7ffffe, v4
	v_cvt_u32_f32_e32 v4, v4
	v_mul_lo_u32 v1, v3, v4
	v_mul_hi_u32 v1, v4, v1
	v_add_u32_e32 v1, v4, v1
	v_mul_hi_u32 v1, v5, v1
	v_mul_lo_u32 v3, v1, v2
	v_sub_u32_e32 v3, v5, v3
	v_add_u32_e32 v4, 1, v1
	v_cmp_ge_u32_e32 vcc, v3, v2
	s_nop 1
	v_cndmask_b32_e32 v1, v1, v4, vcc
	v_sub_u32_e32 v4, v3, v2
	v_cndmask_b32_e32 v3, v3, v4, vcc
	v_add_u32_e32 v4, 1, v1
	v_cmp_ge_u32_e32 vcc, v3, v2
	v_add_u32_e32 v3, 1, v5
	s_nop 0
	v_cndmask_b32_e32 v1, v1, v4, vcc
	v_mul_lo_u32 v4, v2, v1
	v_add_u32_e32 v2, v4, v2
	v_cmp_ne_u32_e32 vcc, v3, v2
	s_and_saveexec_b64 s[4:5], vcc
	s_xor_b64 s[4:5], exec, s[4:5]
	s_cbranch_execz .LBB0_559
	v_readlane_b32 s6, v255, 0
	s_waitcnt lgkmcnt(0)
	v_mov_b32_e32 v0, 0
	v_readlane_b32 s7, v255, 1
	s_nop 4
	buffer_inv sc1
	global_load_dword v2, v0, s[6:7] sc1
	s_waitcnt vmcnt(0)
	v_cmp_eq_u32_e32 vcc, v2, v1
	s_and_saveexec_b64 s[6:7], vcc
	s_cbranch_execz .LBB0_558
	s_mov_b32 s28, 1
	s_mov_b64 s[10:11], 0
	s_branch .LBB0_549

.LBB0_638:
	s_or_b64 exec, exec, s[4:5]
	v_cvt_f32_u32_e32 v4, v2
	s_waitcnt vmcnt(0)
	v_readfirstlane_b32 s2, v3
	v_sub_u32_e32 v3, 0, v2
	v_rcp_iflag_f32_e32 v4, v4
	v_add_u32_e32 v5, s2, v1
	v_mul_f32_e32 v4, 0x4f7ffffe, v4
	v_cvt_u32_f32_e32 v4, v4
	v_mul_lo_u32 v1, v3, v4
	v_mul_hi_u32 v1, v4, v1
	v_add_u32_e32 v1, v4, v1
	v_mul_hi_u32 v1, v5, v1
	v_mul_lo_u32 v3, v1, v2
	v_sub_u32_e32 v3, v5, v3
	v_add_u32_e32 v4, 1, v1
	v_cmp_ge_u32_e32 vcc, v3, v2
	s_nop 1
	v_cndmask_b32_e32 v1, v1, v4, vcc
	v_sub_u32_e32 v4, v3, v2
	v_cndmask_b32_e32 v3, v3, v4, vcc
	v_add_u32_e32 v4, 1, v1
	v_cmp_ge_u32_e32 vcc, v3, v2
	v_add_u32_e32 v3, 1, v5
	s_nop 0
	v_cndmask_b32_e32 v1, v1, v4, vcc
	v_mul_lo_u32 v4, v2, v1
	v_add_u32_e32 v2, v4, v2
	v_cmp_ne_u32_e32 vcc, v3, v2
	s_and_saveexec_b64 s[4:5], vcc
	s_xor_b64 s[4:5], exec, s[4:5]
	s_cbranch_execz .LBB0_652
	v_readlane_b32 s6, v255, 0
	s_waitcnt lgkmcnt(0)
	v_mov_b32_e32 v0, 0
	v_readlane_b32 s7, v255, 1
	s_nop 4
	buffer_inv sc1
	global_load_dword v2, v0, s[6:7] sc1
	s_waitcnt vmcnt(0)
	v_cmp_eq_u32_e32 vcc, v2, v1
	s_and_saveexec_b64 s[6:7], vcc
	s_cbranch_execz .LBB0_651
	s_mov_b32 s2, 1
	s_mov_b64 s[10:11], 0
	s_branch .LBB0_642

.LBB0_711:
	s_or_b64 exec, exec, s[6:7]
	v_cvt_f32_u32_e32 v4, v2
	s_waitcnt vmcnt(0)
	v_readfirstlane_b32 s2, v3
	v_sub_u32_e32 v3, 0, v2
	v_rcp_iflag_f32_e32 v4, v4
	v_add_u32_e32 v5, s2, v1
	v_mul_f32_e32 v4, 0x4f7ffffe, v4
	v_cvt_u32_f32_e32 v4, v4
	v_mul_lo_u32 v1, v3, v4
	v_mul_hi_u32 v1, v4, v1
	v_add_u32_e32 v1, v4, v1
	v_mul_hi_u32 v1, v5, v1
	v_mul_lo_u32 v3, v1, v2
	v_sub_u32_e32 v3, v5, v3
	v_add_u32_e32 v4, 1, v1
	v_cmp_ge_u32_e32 vcc, v3, v2
	s_nop 1
	v_cndmask_b32_e32 v1, v1, v4, vcc
	v_sub_u32_e32 v4, v3, v2
	v_cndmask_b32_e32 v3, v3, v4, vcc
	v_add_u32_e32 v4, 1, v1
	v_cmp_ge_u32_e32 vcc, v3, v2
	v_add_u32_e32 v3, 1, v5
	s_nop 0
	v_cndmask_b32_e32 v1, v1, v4, vcc
	v_mul_lo_u32 v4, v2, v1
	v_add_u32_e32 v2, v4, v2
	v_cmp_ne_u32_e32 vcc, v3, v2
	s_and_saveexec_b64 s[6:7], vcc
	s_xor_b64 s[6:7], exec, s[6:7]
	s_cbranch_execz .LBB0_725
	s_waitcnt lgkmcnt(0)
	v_mov_b32_e32 v0, 0
	buffer_inv sc1
	global_load_dword v2, v0, s[34:35] sc1
	s_waitcnt vmcnt(0)
	v_cmp_eq_u32_e32 vcc, v2, v1
	s_and_saveexec_b64 s[10:11], vcc
	s_cbranch_execz .LBB0_724
	s_mov_b32 s2, 1
	s_mov_b64 s[12:13], 0
	s_branch .LBB0_715

.LBB0_724:
	s_or_b64 exec, exec, s[10:11]
	s_waitcnt vmcnt(0)
	s_nop 0
	s_waitcnt vmcnt(0)

.LBB0_802:
	s_or_b64 exec, exec, s[4:5]
	v_cvt_f32_u32_e32 v4, v2
	s_waitcnt vmcnt(0)
	v_readfirstlane_b32 s2, v3
	v_sub_u32_e32 v3, 0, v2
	v_rcp_iflag_f32_e32 v4, v4
	v_add_u32_e32 v5, s2, v1
	v_mul_f32_e32 v4, 0x4f7ffffe, v4
	v_cvt_u32_f32_e32 v4, v4
	v_mul_lo_u32 v1, v3, v4
	v_mul_hi_u32 v1, v4, v1
	v_add_u32_e32 v1, v4, v1
	v_mul_hi_u32 v1, v5, v1
	v_mul_lo_u32 v3, v1, v2
	v_sub_u32_e32 v3, v5, v3
	v_add_u32_e32 v4, 1, v1
	v_cmp_ge_u32_e32 vcc, v3, v2
	s_nop 1
	v_cndmask_b32_e32 v1, v1, v4, vcc
	v_sub_u32_e32 v4, v3, v2
	v_cndmask_b32_e32 v3, v3, v4, vcc
	v_add_u32_e32 v4, 1, v1
	v_cmp_ge_u32_e32 vcc, v3, v2
	v_add_u32_e32 v3, 1, v5
	s_nop 0
	v_cndmask_b32_e32 v1, v1, v4, vcc
	v_mul_lo_u32 v4, v2, v1
	v_add_u32_e32 v2, v4, v2
	v_cmp_ne_u32_e32 vcc, v3, v2
	s_and_saveexec_b64 s[4:5], vcc
	s_xor_b64 s[4:5], exec, s[4:5]
	s_cbranch_execz .LBB0_816
	s_waitcnt lgkmcnt(0)
	v_mov_b32_e32 v0, 0
	buffer_inv sc1
	global_load_dword v2, v0, s[34:35] sc1
	s_waitcnt vmcnt(0)
	v_cmp_eq_u32_e32 vcc, v2, v1
	s_and_saveexec_b64 s[6:7], vcc
	s_cbranch_execz .LBB0_815
	s_mov_b32 s2, 1
	s_mov_b64 s[10:11], 0
	s_branch .LBB0_806
